# speedup vs baseline: 1.0121x; 1.0029x over previous
; #define IDX_STAGE(c_) do { if ((c_) + 1 < nch) { *(u32x4*)(kt_l + (((c_) + 1) & 1) * 8192 + tid * 16) = st0; \
;           if ((c_) + 2 < nch) st0 = *(const u32x4*)(kbase + (size_t)(((c_) + 2) * 32 + j0) * 128 + cch); } } while (0)
; __device__ __forceinline__ void indexer_phase(const Params& P, char* lds) {
;     ...
;       const u16* kbase = P_kidx + (size_t)b * SEQ * 128;
;       const int j0 = tid >> 4, p0 = tid & 15;
;       const int cch = (p0 ^ (j0 & 15)) * 8;
;       u32x4 st0;
;       st0 = *(const u32x4*)(kbase + (size_t)(j0) * 128 + cch);
;       const int boff = r32 * 256;
;       __syncthreads();
;       *(u32x4*)(kt_l + tid * 16) = st0;
;       if (nch > 1) st0 = *(const u32x4*)(kbase + (size_t)(32 + j0) * 128 + cch);
;       __syncthreads();
;     ...
;       f32x16 xa0, xa1, ya0, ya1;
;       IDX_STAGE(0); IDX_MMA(xa0, xa1, 0);
;       __syncthreads();
;       for (int c = 1; c < nch; c += 2) {
.LBB0_466:
	v_add_u32_e32 v32, v188, v193
	ds_read_b128 v[48:51], v32
	v_add_u32_e32 v203, v188, v196
	ds_read_b128 v[204:207], v203
	v_add_u32_e32 v32, v188, v194
	ds_read_b128 v[180:183], v32
	s_waitcnt lgkmcnt(2)
	v_mfma_f32_32x32x16_bf16 v[32:47], v[96:99], v[48:51], 0
	v_add_u32_e32 v203, v188, v198
	s_and_b64 vcc, exec, s[8:9]
	v_mfma_f32_32x32x16_bf16 v[48:63], v[128:131], v[48:51], 0
	s_waitcnt lgkmcnt(0)
	v_mfma_f32_32x32x16_bf16 v[32:47], v[100:103], v[180:183], v[32:47]
	v_mfma_f32_32x32x16_bf16 v[48:63], v[132:135], v[180:183], v[48:63]
	v_add_u32_e32 v180, v188, v195
	ds_read_b128 v[180:183], v180
	s_waitcnt lgkmcnt(0)
	v_mfma_f32_32x32x16_bf16 v[32:47], v[104:107], v[180:183], v[32:47]
	v_mfma_f32_32x32x16_bf16 v[48:63], v[136:139], v[180:183], v[48:63]
	v_add_u32_e32 v180, v188, v197
	ds_read_b128 v[180:183], v180
	v_mfma_f32_32x32x16_bf16 v[32:47], v[108:111], v[204:207], v[32:47]
	v_mfma_f32_32x32x16_bf16 v[48:63], v[140:143], v[204:207], v[48:63]
	ds_read_b128 v[204:207], v203
	v_add_u32_e32 v203, v188, v200
	s_waitcnt lgkmcnt(1)
	v_mfma_f32_32x32x16_bf16 v[32:47], v[112:115], v[180:183], v[32:47]
	v_mfma_f32_32x32x16_bf16 v[48:63], v[144:147], v[180:183], v[48:63]
	v_add_u32_e32 v180, v188, v199
	ds_read_b128 v[180:183], v180
	s_waitcnt lgkmcnt(1)
	v_mfma_f32_32x32x16_bf16 v[32:47], v[116:119], v[204:207], v[32:47]
	v_mfma_f32_32x32x16_bf16 v[48:63], v[148:151], v[204:207], v[48:63]
	ds_read_b128 v[204:207], v203
	s_waitcnt lgkmcnt(0)
	s_barrier
	v_mfma_f32_32x32x16_bf16 v[32:47], v[120:123], v[180:183], v[32:47]
	v_mfma_f32_32x32x16_bf16 v[48:63], v[152:155], v[180:183], v[48:63]
	v_mfma_f32_32x32x16_bf16 v[32:47], v[124:127], v[204:207], v[32:47]
	v_mfma_f32_32x32x16_bf16 v[48:63], v[156:159], v[204:207], v[48:63]
	s_cbranch_vccnz .LBB0_482
	v_and_b32_e32 v1, 64, v202
	v_xor_b32_e32 v0, 32, v202
	v_add_u32_e32 v1, 64, v1
	v_cmp_lt_i32_e32 vcc, v0, v1
	v_lshl_add_u64 v[180:181], s[12:13], 0, v[168:169]
	s_add_i32 s12, s14, -2
	v_cndmask_b32_e32 v0, v202, v0, vcc
	v_lshlrev_b32_e32 v203, 2, v0
	s_mov_b32 s15, 4
	s_movk_i32 s13, 0x2000
	v_add_u32_e32 v244, 0x22010, v170
	v_add_u32_e32 v237, v244, v193
	v_add_u32_e32 v238, v244, v194
	v_add_u32_e32 v239, v244, v195
	v_add_u32_e32 v240, v244, v196
	v_add_u32_e32 v241, v244, v197
	v_add_u32_e32 v242, v244, v198
	v_add_u32_e32 v243, v244, v199
	v_add_u32_e32 v244, v244, v200
	v_add_u32_e32 v245, v188, v193
	v_add_u32_e32 v246, v188, v194
	v_add_u32_e32 v247, v188, v195
	v_add_u32_e32 v248, v188, v196
	v_add_u32_e32 v249, v188, v197
	v_add_u32_e32 v251, v188, v198
	v_add_u32_e32 v252, v188, v199
	v_add_u32_e32 v253, v188, v200
	v_mov_b32_e32 v204, v189
	v_mov_b32_e32 v182, v171

; #define IDX_STAGE(c_) do { if ((c_) + 1 < nch) { *(u32x4*)(kt_l + (((c_) + 1) & 1) * 8192 + tid * 16) = st0; \
;           if ((c_) + 2 < nch) st0 = *(const u32x4*)(kbase + (size_t)(((c_) + 2) * 32 + j0) * 128 + cch); } } while (0)
; __device__ __forceinline__ void indexer_phase(const Params& P, char* lds) {
;     ...
;         IDX_STAGE(c); IDX_MMA(ya0, ya1, c); IDX_RED(xa0, xa1, c - 1);
.LBB0_471:
	s_and_b32 s0, s13, 0x2000
	s_add_i32 s16, s0, 16
	s_add_i32 s16, s16, 0x20000
	ds_read_b128 v[16:19], v237
	ds_read_b128 v[206:209], v238
	ds_read_b128 v[210:213], v239
	ds_read_b128 v[214:217], v240
	ds_read_b128 v[218:221], v241
	ds_read_b128 v[222:225], v242
	ds_read_b128 v[226:229], v243
	ds_read_b128 v[230:233], v244
	s_waitcnt lgkmcnt(7)
	v_mfma_f32_32x32x16_bf16 v[0:15], v[96:99], v[16:19], 0
	v_max_f32_e32 v183, 0, v32
	v_fma_f32 v183, v92, v183, 0
	v_max_f32_e32 v236, 0, v34
	v_max_f32_e32 v205, 0, v48
	v_fmac_f32_e32 v183, v94, v236
	v_mfma_f32_32x32x16_bf16 v[16:31], v[128:131], v[16:19], 0
	v_max_f32_e32 v236, v50, v50
	v_fma_f32 v205, v88, v205, 0
	v_max_f32_e32 v234, 0, v33
	v_fma_f32 v234, v93, v234, 0
	v_max_f32_e32 v235, 0, v49
	s_waitcnt lgkmcnt(6)
	v_mfma_f32_32x32x16_bf16 v[0:15], v[100:103], v[206:209], v[0:15]
	v_fma_f32 v235, v89, v235, 0
	v_mfma_f32_32x32x16_bf16 v[16:31], v[132:135], v[206:209], v[16:31]
	v_max_f32_e32 v206, 0, v236
	v_fmac_f32_e32 v205, v90, v206
	v_max_f32_e32 v206, 0, v35
	v_fmac_f32_e32 v234, v95, v206
	v_max_f32_e32 v206, 0, v51
	v_fmac_f32_e32 v235, v91, v206
	v_max_f32_e32 v206, 0, v36
	v_fmac_f32_e32 v183, v84, v206
	v_max_f32_e32 v206, 0, v52
	v_fmac_f32_e32 v205, v80, v206
	v_max_f32_e32 v206, 0, v37
	v_fmac_f32_e32 v234, v85, v206
	v_max_f32_e32 v206, 0, v53
	s_waitcnt lgkmcnt(5)
	v_mfma_f32_32x32x16_bf16 v[0:15], v[104:107], v[210:213], v[0:15]
	v_fmac_f32_e32 v235, v81, v206
	v_max_f32_e32 v206, 0, v38
	v_fmac_f32_e32 v183, v86, v206
	v_max_f32_e32 v206, 0, v54
	v_fmac_f32_e32 v205, v82, v206
	v_mfma_f32_32x32x16_bf16 v[16:31], v[136:139], v[210:213], v[16:31]
	v_max_f32_e32 v206, 0, v39
	v_fmac_f32_e32 v234, v87, v206
	v_max_f32_e32 v206, 0, v55
	v_fmac_f32_e32 v235, v83, v206
	s_waitcnt lgkmcnt(4)
	v_mfma_f32_32x32x16_bf16 v[0:15], v[108:111], v[214:217], v[0:15]
	v_max_f32_e32 v206, 0, v40
	v_fmac_f32_e32 v183, v72, v206
	v_max_f32_e32 v206, 0, v56
	s_waitcnt vmcnt(1)
	v_fmac_f32_e32 v205, v76, v206
	v_max_f32_e32 v206, 0, v41
	v_mfma_f32_32x32x16_bf16 v[16:31], v[140:143], v[214:217], v[16:31]
	v_fmac_f32_e32 v234, v73, v206
	v_max_f32_e32 v206, 0, v57
	v_fmac_f32_e32 v235, v77, v206
	v_max_f32_e32 v206, 0, v42
	v_fmac_f32_e32 v183, v74, v206
	s_waitcnt lgkmcnt(3)
	v_mfma_f32_32x32x16_bf16 v[0:15], v[112:115], v[218:221], v[0:15]
	v_max_f32_e32 v206, 0, v58
	v_fmac_f32_e32 v205, v78, v206
	v_max_f32_e32 v206, 0, v43
	v_fmac_f32_e32 v234, v75, v206
	v_mfma_f32_32x32x16_bf16 v[16:31], v[144:147], v[218:221], v[16:31]
	v_max_f32_e32 v206, 0, v59
	v_fmac_f32_e32 v235, v79, v206
	v_max_f32_e32 v206, 0, v44
	v_fmac_f32_e32 v183, v64, v206
	v_max_f32_e32 v206, 0, v60
	s_waitcnt lgkmcnt(2)
	v_mfma_f32_32x32x16_bf16 v[0:15], v[116:119], v[222:225], v[0:15]
	s_waitcnt vmcnt(0)
	v_fmac_f32_e32 v205, v68, v206
	v_max_f32_e32 v206, 0, v45
	v_fmac_f32_e32 v234, v65, v206
	v_max_f32_e32 v206, 0, v61
	v_fmac_f32_e32 v235, v69, v206
	v_mfma_f32_32x32x16_bf16 v[16:31], v[148:151], v[222:225], v[16:31]
	v_max_f32_e32 v206, 0, v46
	v_fmac_f32_e32 v183, v66, v206
	v_max_f32_e32 v206, 0, v62
	v_fmac_f32_e32 v205, v70, v206
	s_waitcnt lgkmcnt(1)
	v_mfma_f32_32x32x16_bf16 v[0:15], v[120:123], v[226:229], v[0:15]
	v_max_f32_e32 v206, 0, v47
	v_fmac_f32_e32 v234, v67, v206
	v_max_f32_e32 v206, 0, v63
	v_fmac_f32_e32 v235, v71, v206
	v_add_f32_e32 v183, v183, v205
	v_add_f32_e32 v205, v234, v235
	v_mfma_f32_32x32x16_bf16 v[16:31], v[152:155], v[226:229], v[16:31]
	v_add_f32_e32 v183, v183, v205
	ds_bpermute_b32 v205, v203, v183
	s_waitcnt lgkmcnt(1)
	v_mfma_f32_32x32x16_bf16 v[0:15], v[124:127], v[230:233], v[0:15]
	v_mfma_f32_32x32x16_bf16 v[16:31], v[156:159], v[230:233], v[16:31]
	s_and_saveexec_b64 s[0:1], s[4:5]
	s_cbranch_execz .LBB0_473
	s_waitcnt lgkmcnt(0)
	v_add_f32_e32 v183, v183, v205
	ds_write_b32 v204, v183

; #define IDX_STAGE(c_) do { if ((c_) + 1 < nch) { *(u32x4*)(kt_l + (((c_) + 1) & 1) * 8192 + tid * 16) = st0; \
;           if ((c_) + 2 < nch) st0 = *(const u32x4*)(kbase + (size_t)(((c_) + 2) * 32 + j0) * 128 + cch); } } while (0)
; __device__ __forceinline__ void indexer_phase(const Params& P, char* lds) {
;     ...
;           IDX_STAGE(c + 1); IDX_MMA(xa0, xa1, c + 1); IDX_RED(ya0, ya1, c);
.LBB0_477:
	ds_read_b128 v[48:51], v245
	ds_read_b128 v[206:209], v246
	ds_read_b128 v[210:213], v247
	ds_read_b128 v[214:217], v248
	ds_read_b128 v[218:221], v249
	ds_read_b128 v[222:225], v251
	ds_read_b128 v[226:229], v252
	ds_read_b128 v[230:233], v253
	s_waitcnt lgkmcnt(7)
	v_mfma_f32_32x32x16_bf16 v[32:47], v[96:99], v[48:51], 0
	v_max_f32_e32 v183, 0, v0
	v_fma_f32 v183, v92, v183, 0
	v_max_f32_e32 v236, 0, v2
	v_max_f32_e32 v205, 0, v16
	v_fmac_f32_e32 v183, v94, v236
	v_mfma_f32_32x32x16_bf16 v[48:63], v[128:131], v[48:51], 0
	v_max_f32_e32 v236, v18, v18
	v_fma_f32 v205, v88, v205, 0
	v_max_f32_e32 v234, 0, v1
	v_fma_f32 v234, v93, v234, 0
	v_max_f32_e32 v235, 0, v17
	s_waitcnt lgkmcnt(6)
	v_mfma_f32_32x32x16_bf16 v[32:47], v[100:103], v[206:209], v[32:47]
	v_fma_f32 v235, v89, v235, 0
	v_mfma_f32_32x32x16_bf16 v[48:63], v[132:135], v[206:209], v[48:63]
	v_max_f32_e32 v206, 0, v236
	v_fmac_f32_e32 v205, v90, v206
	v_max_f32_e32 v206, 0, v3
	v_fmac_f32_e32 v234, v95, v206
	v_max_f32_e32 v206, 0, v19
	v_fmac_f32_e32 v235, v91, v206
	v_max_f32_e32 v206, 0, v4
	v_fmac_f32_e32 v183, v84, v206
	v_max_f32_e32 v206, 0, v20
	v_fmac_f32_e32 v205, v80, v206
	v_max_f32_e32 v206, 0, v5
	v_fmac_f32_e32 v234, v85, v206
	v_max_f32_e32 v206, 0, v21
	s_waitcnt lgkmcnt(5)
	v_mfma_f32_32x32x16_bf16 v[32:47], v[104:107], v[210:213], v[32:47]
	v_fmac_f32_e32 v235, v81, v206
	v_max_f32_e32 v206, 0, v6
	v_fmac_f32_e32 v183, v86, v206
	v_max_f32_e32 v206, 0, v22
	v_fmac_f32_e32 v205, v82, v206
	v_mfma_f32_32x32x16_bf16 v[48:63], v[136:139], v[210:213], v[48:63]
	v_max_f32_e32 v206, 0, v7
	v_fmac_f32_e32 v234, v87, v206
	v_max_f32_e32 v206, 0, v23
	v_fmac_f32_e32 v235, v83, v206
	s_waitcnt lgkmcnt(4)
	v_mfma_f32_32x32x16_bf16 v[32:47], v[108:111], v[214:217], v[32:47]
	v_max_f32_e32 v206, 0, v8
	v_fmac_f32_e32 v183, v72, v206
	v_max_f32_e32 v206, 0, v24
	v_fmac_f32_e32 v205, v76, v206
	v_max_f32_e32 v206, 0, v9
	v_mfma_f32_32x32x16_bf16 v[48:63], v[140:143], v[214:217], v[48:63]
	v_fmac_f32_e32 v234, v73, v206
	v_max_f32_e32 v206, 0, v25
	v_fmac_f32_e32 v235, v77, v206
	v_max_f32_e32 v206, 0, v10
	v_fmac_f32_e32 v183, v74, v206
	s_waitcnt lgkmcnt(3)
	v_mfma_f32_32x32x16_bf16 v[32:47], v[112:115], v[218:221], v[32:47]
	v_max_f32_e32 v206, 0, v26
	v_fmac_f32_e32 v205, v78, v206
	v_max_f32_e32 v206, 0, v11
	v_fmac_f32_e32 v234, v75, v206
	v_mfma_f32_32x32x16_bf16 v[48:63], v[144:147], v[218:221], v[48:63]
	v_max_f32_e32 v206, 0, v27
	v_fmac_f32_e32 v235, v79, v206
	v_max_f32_e32 v206, 0, v12
	v_fmac_f32_e32 v183, v64, v206
	v_max_f32_e32 v206, 0, v28
	s_waitcnt lgkmcnt(2)
	v_mfma_f32_32x32x16_bf16 v[32:47], v[116:119], v[222:225], v[32:47]
	v_fmac_f32_e32 v205, v68, v206
	v_max_f32_e32 v206, 0, v13
	v_fmac_f32_e32 v234, v65, v206
	v_max_f32_e32 v206, 0, v29
	v_fmac_f32_e32 v235, v69, v206
	v_mfma_f32_32x32x16_bf16 v[48:63], v[148:151], v[222:225], v[48:63]
	v_max_f32_e32 v206, 0, v14
	v_fmac_f32_e32 v183, v66, v206
	v_max_f32_e32 v206, 0, v30
	v_fmac_f32_e32 v205, v70, v206
	s_waitcnt lgkmcnt(1)
	v_mfma_f32_32x32x16_bf16 v[32:47], v[120:123], v[226:229], v[32:47]
	v_max_f32_e32 v206, 0, v15
	v_fmac_f32_e32 v234, v67, v206
	v_max_f32_e32 v206, 0, v31
	v_fmac_f32_e32 v235, v71, v206
	v_add_f32_e32 v183, v183, v205
	v_add_f32_e32 v205, v234, v235
	v_mfma_f32_32x32x16_bf16 v[48:63], v[152:155], v[226:229], v[48:63]
	v_add_f32_e32 v183, v183, v205
	ds_bpermute_b32 v205, v203, v183
	s_waitcnt lgkmcnt(1)
	v_mfma_f32_32x32x16_bf16 v[32:47], v[124:127], v[230:233], v[32:47]
	v_mfma_f32_32x32x16_bf16 v[48:63], v[156:159], v[230:233], v[48:63]
	s_and_saveexec_b64 s[0:1], s[4:5]
	s_cbranch_execz .LBB0_479
	s_waitcnt lgkmcnt(0)
	v_add_f32_e32 v183, v183, v205
	ds_write_b32 v204, v183 offset:128
